# rwc producers: running pointers instead of per-block 64-bit address math; gdb tile tails batched and branch-free
# speedup vs baseline: 1.0687x; 1.0042x over previous
; #define LAS __attribute__((address_space(3)))
; __device__ __forceinline__ f32x4 mfma16(h8 a, h8 b, f32x4 c) { return __builtin_amdgcn_mfma_f32_16x16x32_f16(a, b, c, 0, 0, 0); }
; __device__ __forceinline__ void phase_gdb(const int wvs, const Params& p, LAS unsigned char* lds, int nwg) {
;     ...
;     for (int tl = w2 * 5; tl < w2 * 5 + 5; ++tl) { const int ti = tl < 1 ? 0 : tl < 3 ? 1 : tl < 6 ? 2 : 3, tj = tl - (ti * (ti + 1)) / 2;
;       f32x4 acc = {0.f, 0.f, 0.f, 0.f};
; #pragma unroll
;       for (int ks = 0; ks < 2; ++ks) { const h8 af = *(const LAS h8*)(R + (ti * 16 + fr) * RP + 64 + ks * 32 + fq * 8); const h8 bf = *(const LAS h8*)(R + (tj * 16 + fr) * RP + 64 + ks * 32 + fq * 8);
;         acc = mfma16(af, bf, acc); }
; #pragma unroll
;       for (int r = 0; r < 4; ++r) { const int i = ti * 16 + fq * 4 + r, j = tj * 16 + fr; M[i * 64 + j] = (j < i) ? bs[i] * acc[r] * __expf(gcs[i] - gcs[j]) : 0.f; } }
.LBB0_890:
	s_or_b64 exec, exec, s[10:11]
	s_add_i32 s13, s13, 1
	v_add_u32_e32 v8, 64, v8
	v_add_u32_e32 v7, 64, v7
	v_add_u32_e32 v6, 16, v6
	s_cmp_eq_u32 s13, 5
	v_add_u32_e32 v0, 0x1100, v0
	s_cbranch_scc1 .LBB0_899
.LBB0_891:
	v_add_u32_e32 v2, s13, v230
	v_cmp_gt_u32_e64 s[8:9], 6, v2
	s_nop 1
	v_cndmask_b32_e64 v3, 3, 2, s[8:9]
	v_cmp_lt_u32_e64 s[8:9], 2, v2
	s_nop 1
	v_cndmask_b32_e64 v3, 1, v3, s[8:9]
	v_cmp_ne_u32_e64 s[8:9], 0, v2
	s_nop 1
	v_cndmask_b32_e64 v12, 0, v3, s[8:9]
	v_add_u32_e32 v2, 1, v12
	v_mul_u32_u24_e32 v2, v2, v12
	v_lshlrev_b32_e32 v11, 4, v12
	v_lshrrev_b32_e32 v10, 1, v2
	v_or_b32_e32 v2, v11, v226
	v_mad_u32_u24 v13, v2, s67, v233
	v_lshlrev_b32_e32 v2, 4, v10
	v_sub_u32_e32 v9, v6, v2
	v_mul_i32_i24_e32 v2, 0xffffef00, v10
	v_add3_u32 v18, v227, v2, v0
	ds_read_b128 v[2:5], v13 offset:16512
	ds_read_b128 v[14:17], v18
	s_waitcnt lgkmcnt(0)
	v_mfma_f32_16x16x32_f16 v[2:5], v[2:5], v[14:17], 0
	ds_read_b128 v[14:17], v13 offset:16576
	ds_read_b128 v[18:21], v18 offset:64
	v_or_b32_e32 v13, v11, v231
	v_cmp_lt_i32_e64 s[8:9], v9, v13
	s_waitcnt lgkmcnt(0)
	v_mfma_f32_16x16x32_f16 v[2:5], v[14:17], v[18:21], v[2:5]
	v_lshlrev_b32_e32 v15, 6, v10
	v_sub_u32_e32 v10, v227, v15
	v_lshl_add_u32 v11, v13, 2, v228
	v_add_u32_e32 v10, v8, v10
	ds_read_b128 v[22:25], v11 offset:34048
	ds_read_b128 v[26:29], v11 offset:34304
	ds_read_b32 v30, v10
	v_lshlrev_b32_e32 v31, 12, v12
	v_sub_u32_e32 v31, v31, v15
	v_add_u32_e32 v31, v227, v31
	v_add_u32_e32 v31, v7, v31
	v_or_b32_e32 v32, 2, v13
	v_or_b32_e32 v33, 3, v13
	v_cmp_lt_i32_e64 s[8:9], v9, v13
	v_cmp_le_i32_e64 s[10:11], v9, v13
	v_cmp_lt_i32_e64 s[18:19], v9, v32
	v_cmp_lt_i32_e64 s[20:21], v9, v33
	s_waitcnt lgkmcnt(0)
	v_sub_f32_e32 v34, v26, v30
	v_sub_f32_e32 v35, v27, v30
	v_sub_f32_e32 v36, v28, v30
	v_sub_f32_e32 v37, v29, v30
	v_mul_f32_e32 v34, 0x3fb8aa3b, v34
	v_mul_f32_e32 v35, 0x3fb8aa3b, v35
	v_mul_f32_e32 v36, 0x3fb8aa3b, v36
	v_mul_f32_e32 v37, 0x3fb8aa3b, v37
	v_exp_f32_e32 v34, v34
	v_exp_f32_e32 v35, v35
	v_exp_f32_e32 v36, v36
	v_exp_f32_e32 v37, v37
	v_mul_f32_e32 v2, v2, v22
	v_mul_f32_e32 v3, v3, v23
	v_mul_f32_e32 v4, v4, v24
	v_mul_f32_e32 v5, v5, v25
	v_mul_f32_e32 v34, v2, v34
	v_mul_f32_e32 v35, v3, v35
	v_mul_f32_e32 v36, v4, v36
	v_mul_f32_e32 v37, v5, v37
	v_cndmask_b32_e64 v34, 0, v34, s[8:9]
	v_cndmask_b32_e64 v35, 0, v35, s[10:11]
	v_cndmask_b32_e64 v36, 0, v36, s[18:19]
	v_cndmask_b32_e64 v37, 0, v37, s[20:21]
	ds_write_b32 v31, v34
	ds_write_b32 v31, v35 offset:256
	ds_write_b32 v31, v36 offset:512
	ds_write_b32 v31, v37 offset:768
	s_branch .LBB0_890

.LBB0_1283:
	v_ashrrev_i32_e32 v13, 31, v12
	v_lshl_add_u64 v[12:13], s[16:17], 0, v[12:13]
	v_mov_b64_e32 v[18:19], s[24:25]
	v_mad_u64_u32 v[18:19], s[44:45], v12, s68, v[18:19]
	v_mov_b32_e32 v16, v19
	v_mad_u64_u32 v[20:21], s[44:45], v13, s68, v[16:17]
	v_mov_b32_e32 v19, v20
	v_mov_b64_e32 v[20:21], s[18:19]
	v_mad_u64_u32 v[20:21], s[44:45], v12, s51, v[20:21]
	v_mov_b32_e32 v16, v21
	v_mad_u64_u32 v[26:27], s[44:45], v13, s51, v[16:17]
	v_mov_b32_e32 v21, v26
	v_lshl_add_u64 v[20:21], v[20:21], 0, s[30:31]
	v_lshl_add_u64 v[20:21], v[20:21], 0, s[26:27]
	v_lshl_add_u64 v[18:19], v[18:19], 0, s[26:27]
	v_lshl_add_u64 v[20:21], v[20:21], 0, v[0:1]
	s_movk_i32 s2, 0x1000
	v_lshl_add_u64 v[18:19], v[18:19], 0, v[0:1]
	v_add_co_u32_e32 v20, vcc, s2, v20
	s_nop 1
	v_addc_co_u32_e32 v21, vcc, 0, v21, vcc
	v_mov_b64_e32 v[80:81], v[18:19]
	v_mov_b64_e32 v[86:87], v[20:21]
	global_load_dwordx2 v[30:31], v[18:19], off
	global_load_dwordx2 v[28:29], v[18:19], off offset:768
	global_load_dwordx2 v[32:33], v[20:21], off
	global_load_dwordx2 v[36:37], v[20:21], off offset:1536
	v_mad_u64_u32 v[18:19], s[44:45], v12, 24, s[14:15]
	v_mov_b32_e32 v12, v19
	v_mad_u64_u32 v[12:13], s[44:45], v13, 24, v[12:13]
	v_mov_b32_e32 v19, v12
	v_mov_b64_e32 v[90:91], v[18:19]
	global_load_dword v34, v[18:19], off
	s_and_b64 vcc, exec, s[6:7]
	s_mov_b64 s[44:45], -1
	s_cbranch_vccnz .LBB0_1289
	s_movk_i32 s2, 0xdff
	v_cmp_lt_u32_e32 vcc, s2, v25
	s_and_saveexec_b64 s[44:45], vcc
	s_xor_b64 s[44:45], exec, s[44:45]
	v_sub_u32_e32 v12, 0x11df, v53
	s_andn2_saveexec_b64 s[44:45], s[44:45]
	v_sub_u32_e32 v12, 0xdf, v53
	s_or_b64 exec, exec, s[44:45]
	s_mov_b64 s[44:45], 0

.LBB0_1291:
	v_ashrrev_i32_e32 v13, 31, v12
	v_lshl_add_u64 v[12:13], s[16:17], 0, v[12:13]
	v_mov_b64_e32 v[18:19], s[24:25]
	v_mad_u64_u32 v[18:19], s[44:45], v12, s68, v[18:19]
	v_mov_b32_e32 v16, v19
	v_mad_u64_u32 v[20:21], s[44:45], v13, s68, v[16:17]
	v_mov_b32_e32 v19, v20
	v_mov_b64_e32 v[20:21], s[18:19]
	v_mad_u64_u32 v[20:21], s[44:45], v12, s51, v[20:21]
	v_mov_b32_e32 v16, v21
	v_mad_u64_u32 v[26:27], s[44:45], v13, s51, v[16:17]
	v_mov_b32_e32 v21, v26
	v_lshl_add_u64 v[20:21], v[20:21], 0, s[30:31]
	v_lshl_add_u64 v[20:21], v[20:21], 0, s[26:27]
	v_lshl_add_u64 v[18:19], v[18:19], 0, s[26:27]
	v_lshl_add_u64 v[20:21], v[20:21], 0, v[0:1]
	s_movk_i32 s2, 0x1000
	v_lshl_add_u64 v[18:19], v[18:19], 0, v[0:1]
	v_add_co_u32_e32 v20, vcc, s2, v20
	s_nop 1
	v_addc_co_u32_e32 v21, vcc, 0, v21, vcc
	v_mov_b64_e32 v[82:83], v[18:19]
	v_mov_b64_e32 v[88:89], v[20:21]
	global_load_dwordx2 v[44:45], v[18:19], off
	global_load_dwordx2 v[42:43], v[18:19], off offset:768
	global_load_dwordx2 v[46:47], v[20:21], off
	global_load_dwordx2 v[48:49], v[20:21], off offset:1536
	v_mad_u64_u32 v[18:19], s[44:45], v12, 24, s[14:15]
	v_mov_b32_e32 v12, v19
	v_mad_u64_u32 v[12:13], s[44:45], v13, 24, v[12:13]
	v_mov_b32_e32 v19, v12
	v_mov_b64_e32 v[92:93], v[18:19]
	global_load_dword v35, v[18:19], off
	s_mov_b64 s[44:45], -1
	s_and_b64 vcc, exec, s[22:23]
	s_cbranch_vccz .LBB0_1297
	s_movk_i32 s2, 0x6ff
	v_cmp_lt_u32_e32 vcc, s2, v39
	s_and_saveexec_b64 s[22:23], vcc
	s_xor_b64 s[22:23], exec, s[22:23]
	v_sub_u32_e32 v12, 0x11df, v54
	s_andn2_saveexec_b64 s[22:23], s[22:23]
	v_sub_u32_e32 v12, 0xdf, v54
	s_or_b64 exec, exec, s[22:23]
	s_mov_b64 s[44:45], 0

; __device__ __forceinline__ void phase_rwc(const int wvs, const Params& p, LAS unsigned char* lds, int layer, int wg0) {
;     ...
;     RW_LOAD(0) RW_DERIVE(0) RW_LOAD(1)
;     __syncthreads();
.LBB0_1299:
	v_ashrrev_i32_e32 v13, 31, v12
	v_lshl_add_u64 v[12:13], s[16:17], 0, v[12:13]
	v_mov_b64_e32 v[18:19], s[24:25]
	v_mad_u64_u32 v[18:19], s[44:45], v12, s68, v[18:19]
	v_mov_b32_e32 v12, v19
	v_mad_u64_u32 v[12:13], s[44:45], v13, s68, v[12:13]
	s_lshl_b32 s2, s48, 4
	v_mov_b32_e32 v19, v12
	s_lshl_b32 s22, s2, 1
	s_mov_b32 s23, s31
	v_lshl_add_u64 v[12:13], v[18:19], 0, s[26:27]
	v_lshl_add_u64 v[12:13], v[12:13], 0, s[22:23]
	v_mov_b32_e32 v11, v1
	v_lshl_add_u64 v[12:13], v[12:13], 0, v[10:11]
	v_mov_b64_e32 v[84:85], v[12:13]
	global_load_dword v65, v[12:13], off offset:1536
	s_add_u32 s20, s20, s22
	s_addc_u32 s21, s21, 0
	v_lshlrev_b32_e32 v12, 1, v17
	v_mov_b32_e32 v13, v1
	v_lshl_add_u64 v[26:27], s[20:21], 0, v[12:13]
	v_readlane_b32 s2, v254, 7
	s_add_u32 s20, s24, s26
	s_addc_u32 s21, s25, s27
	v_add3_u32 v59, s2, v38, v22
	v_readlane_b32 s2, v254, 8
	v_lshlrev_b32_e32 v58, 6, v39
	v_lshlrev_b32_e32 v57, 6, v25
	v_add3_u32 v60, s2, v38, v22
	v_lshl_add_u64 v[38:39], s[20:21], 0, v[0:1]
	s_add_u32 s20, s20, s22
	v_readlane_b32 s2, v254, 6
	s_addc_u32 s21, s21, 0
	v_lshl_add_u64 v[40:41], s[20:21], 0, v[10:11]
	v_lshl_add_u32 v61, v14, 2, s2
	v_sub_u32_e32 v62, 0x121f, v52
	v_sub_u32_e32 v63, 0x121f, v53
	v_sub_u32_e32 v64, 0x11bf, v54
	s_mov_b32 s24, 0
	s_mov_b32 s25, 0
	s_waitcnt lgkmcnt(0)
	s_barrier
	s_branch .LBB0_1302

.LBB0_1302:
	s_waitcnt vmcnt(9)
	v_cvt_f32_f16_sdwa v21, v28 dst_sel:DWORD dst_unused:UNUSED_PAD src0_sel:WORD_1
	v_cvt_f32_f16_e32 v20, v28
	s_waitcnt vmcnt(7)
	v_cvt_f32_f16_sdwa v51, v36 dst_sel:DWORD dst_unused:UNUSED_PAD src0_sel:WORD_1
	v_cvt_f32_f16_e32 v50, v36
	v_cvt_f32_f16_sdwa v69, v37 dst_sel:DWORD dst_unused:UNUSED_PAD src0_sel:WORD_1
	v_pk_mul_f32 v[12:13], v[2:3], v[20:21]
	v_cvt_f32_f16_e32 v68, v37
	v_cvt_f32_f16_e32 v10, v32
	v_cvt_f32_f16_sdwa v11, v32 dst_sel:DWORD dst_unused:UNUSED_PAD src0_sel:WORD_1
	s_waitcnt vmcnt(1)
	v_pk_mul_f32 v[14:15], v[12:13], v[34:35] op_sel_hi:[1,0]
	v_cvt_f32_f16_e32 v12, v33
	v_cvt_f32_f16_sdwa v13, v33 dst_sel:DWORD dst_unused:UNUSED_PAD src0_sel:WORD_1
	v_cvt_f32_f16_sdwa v67, v29 dst_sel:DWORD dst_unused:UNUSED_PAD src0_sel:WORD_1
	v_cvt_f32_f16_e32 v66, v29
	v_xor_b32_e32 v22, 0x80000000, v50
	v_xor_b32_e32 v23, 0x80000000, v51
	v_xor_b32_e32 v24, 0x80000000, v68
	v_xor_b32_e32 v25, 0x80000000, v69
	v_pk_add_f32 v[50:51], v[50:51], -1.0 op_sel_hi:[1,0]
	v_pk_add_f32 v[68:69], v[68:69], -1.0 op_sel_hi:[1,0]
	v_mul_f32_e32 v10, 0xbfb8aa3b, v10
	v_mul_f32_e32 v11, 0xbfb8aa3b, v11
	v_mul_f32_e32 v12, 0xbfb8aa3b, v12
	v_mul_f32_e32 v13, 0xbfb8aa3b, v13
	v_pk_fma_f32 v[68:69], v[8:9], v[68:69], 1.0 op_sel_hi:[1,1,0]
	v_pk_fma_f32 v[50:51], v[6:7], v[50:51], 1.0 op_sel_hi:[1,1,0]
	v_exp_f32_e32 v10, v10
	v_exp_f32_e32 v11, v11
	v_cvt_f32_f16_sdwa v19, v30 dst_sel:DWORD dst_unused:UNUSED_PAD src0_sel:WORD_1
	v_cvt_f32_f16_e32 v18, v30
	v_exp_f32_e32 v12, v12
	v_exp_f32_e32 v13, v13
	v_pk_mul_f32 v[16:17], v[4:5], v[66:67]
	v_pk_mul_f32 v[68:69], v[68:69], v[66:67]
	v_pk_mul_f32 v[66:67], v[50:51], v[20:21]
	v_cvt_f32_f16_sdwa v21, v31 dst_sel:DWORD dst_unused:UNUSED_PAD src0_sel:WORD_1
	v_cvt_f32_f16_e32 v20, v31
	v_pk_mul_f32 v[16:17], v[16:17], v[34:35] op_sel_hi:[1,0]
	v_pk_mul_f32 v[22:23], v[14:15], v[22:23]
	v_pk_mul_f32 v[24:25], v[16:17], v[24:25]
	ds_write_b128 v55, v[10:13] offset:43008
	ds_write_b128 v55, v[14:17] offset:51200
	ds_write_b128 v55, v[22:25] offset:59392
	ds_write_b128 v60, v[18:21]
	v_cvt_f32_f16_sdwa v21, v42 dst_sel:DWORD dst_unused:UNUSED_PAD src0_sel:WORD_1
	v_cvt_f32_f16_e32 v20, v42
	v_cvt_f32_f16_e32 v10, v46
	v_cvt_f32_f16_sdwa v11, v46 dst_sel:DWORD dst_unused:UNUSED_PAD src0_sel:WORD_1
	ds_write_b128 v59, v[66:69]
	v_pk_mul_f32 v[12:13], v[2:3], v[20:21]
	v_cvt_f32_f16_sdwa v51, v48 dst_sel:DWORD dst_unused:UNUSED_PAD src0_sel:WORD_1
	v_pk_mul_f32 v[14:15], v[12:13], v[34:35] op_sel:[0,1]
	v_cvt_f32_f16_e32 v12, v47
	v_cvt_f32_f16_sdwa v13, v47 dst_sel:DWORD dst_unused:UNUSED_PAD src0_sel:WORD_1
	v_cvt_f32_f16_e32 v50, v48
	v_cvt_f32_f16_sdwa v69, v49 dst_sel:DWORD dst_unused:UNUSED_PAD src0_sel:WORD_1
	v_cvt_f32_f16_e32 v68, v49
	v_cvt_f32_f16_sdwa v67, v43 dst_sel:DWORD dst_unused:UNUSED_PAD src0_sel:WORD_1
	v_cvt_f32_f16_e32 v66, v43
	v_mul_f32_e32 v10, 0xbfb8aa3b, v10
	v_mul_f32_e32 v11, 0xbfb8aa3b, v11
	v_mul_f32_e32 v12, 0xbfb8aa3b, v12
	v_mul_f32_e32 v13, 0xbfb8aa3b, v13
	v_exp_f32_e32 v10, v10
	v_exp_f32_e32 v11, v11
	v_exp_f32_e32 v12, v12
	v_exp_f32_e32 v13, v13
	v_xor_b32_e32 v22, 0x80000000, v50
	v_xor_b32_e32 v23, 0x80000000, v51
	v_xor_b32_e32 v24, 0x80000000, v68
	v_xor_b32_e32 v25, 0x80000000, v69
	v_pk_add_f32 v[50:51], v[50:51], -1.0 op_sel_hi:[1,0]
	v_pk_add_f32 v[68:69], v[68:69], -1.0 op_sel_hi:[1,0]
	v_pk_mul_f32 v[16:17], v[4:5], v[66:67]
	v_pk_fma_f32 v[68:69], v[8:9], v[68:69], 1.0 op_sel_hi:[1,1,0]
	v_pk_fma_f32 v[50:51], v[6:7], v[50:51], 1.0 op_sel_hi:[1,1,0]
	s_cmpk_gt_u32 s25, 0x85
	v_cvt_f32_f16_sdwa v19, v44 dst_sel:DWORD dst_unused:UNUSED_PAD src0_sel:WORD_1
	v_cvt_f32_f16_e32 v18, v44
	v_pk_mul_f32 v[16:17], v[16:17], v[34:35] op_sel:[0,1]
	v_pk_mul_f32 v[68:69], v[68:69], v[66:67]
	v_pk_mul_f32 v[66:67], v[50:51], v[20:21]
	v_cvt_f32_f16_sdwa v21, v45 dst_sel:DWORD dst_unused:UNUSED_PAD src0_sel:WORD_1
	v_cvt_f32_f16_e32 v20, v45
	s_cselect_b64 s[20:21], -1, 0
	v_pk_mul_f32 v[24:25], v[16:17], v[24:25]
	v_pk_mul_f32 v[22:23], v[14:15], v[22:23]
	ds_write_b128 v55, v[10:13] offset:47104
	ds_write_b128 v55, v[14:17] offset:55296
	s_waitcnt vmcnt(0)
	v_cvt_f32_f16_sdwa v11, v65 dst_sel:DWORD dst_unused:UNUSED_PAD src0_sel:WORD_1
	v_cvt_f32_f16_e32 v10, v65
	s_and_b64 vcc, exec, s[20:21]
	ds_write_b128 v55, v[22:25] offset:63488
	ds_write_b128 v59, v[66:69] offset:4096
	ds_write_b128 v60, v[18:21] offset:4096
	ds_write2_b32 v61, v10, v11 offset1:32
	s_cbranch_vccnz .LBB0_1320
	s_mov_b32 s2, 32
	s_and_b64 vcc, exec, s[6:7]
	s_cbranch_vccnz .Lrwp_a
	s_movk_i32 s2, 0xffe0
	s_cmp_eq_u32 s25, 6
	s_cbranch_scc0 .Lrwp_a
	s_movk_i32 s2, 0x10e0
.Lrwp_a:
	s_mul_i32 s22, s2, 0x900
	s_ashr_i32 s23, s22, 31
	v_lshl_add_u64 v[80:81], v[80:81], 0, s[22:23]
	v_lshl_add_u64 v[82:83], v[82:83], 0, s[22:23]
	v_lshl_add_u64 v[84:85], v[84:85], 0, s[22:23]
	s_mul_i32 s22, s2, 0x1c00
	s_ashr_i32 s23, s22, 31
	v_lshl_add_u64 v[86:87], v[86:87], 0, s[22:23]
	v_lshl_add_u64 v[88:89], v[88:89], 0, s[22:23]
	s_mul_i32 s22, s2, 24
	s_ashr_i32 s23, s22, 31
	v_lshl_add_u64 v[90:91], v[90:91], 0, s[22:23]
	v_lshl_add_u64 v[92:93], v[92:93], 0, s[22:23]
	global_load_dwordx2 v[28:29], v[80:81], off offset:768
	global_load_dwordx2 v[30:31], v[80:81], off
	global_load_dwordx2 v[32:33], v[86:87], off
	global_load_dwordx2 v[36:37], v[86:87], off offset:1536
	global_load_dword v34, v[90:91], off
	global_load_dwordx2 v[42:43], v[82:83], off offset:768
	global_load_dwordx2 v[44:45], v[82:83], off
	global_load_dwordx2 v[46:47], v[88:89], off
	global_load_dwordx2 v[48:49], v[88:89], off offset:1536
	global_load_dword v35, v[92:93], off
	global_load_dword v65, v[84:85], off offset:1536

.LBB0_1334:
.LBB0_1335:
	s_lshl_b32 s22, s25, 5
	s_mov_b32 s2, 32
	s_and_b64 vcc, exec, s[6:7]
	s_cbranch_vccnz .Lrwp_b
	s_movk_i32 s2, 0xffe0
	s_cmp_eq_u32 s25, 5
	s_cbranch_scc0 .Lrwp_b
	s_movk_i32 s2, 0x10e0
.Lrwp_b:
	s_mul_i32 s20, s2, 0x900
	s_ashr_i32 s21, s20, 31
	v_lshl_add_u64 v[80:81], v[80:81], 0, s[20:21]
	v_lshl_add_u64 v[82:83], v[82:83], 0, s[20:21]
	v_lshl_add_u64 v[84:85], v[84:85], 0, s[20:21]
	s_mul_i32 s20, s2, 0x1c00
	s_ashr_i32 s21, s20, 31
	v_lshl_add_u64 v[86:87], v[86:87], 0, s[20:21]
	v_lshl_add_u64 v[88:89], v[88:89], 0, s[20:21]
	s_mul_i32 s20, s2, 24
	s_ashr_i32 s21, s20, 31
	v_lshl_add_u64 v[90:91], v[90:91], 0, s[20:21]
	v_lshl_add_u64 v[92:93], v[92:93], 0, s[20:21]
	global_load_dwordx2 v[28:29], v[80:81], off offset:768
	global_load_dwordx2 v[30:31], v[80:81], off
	global_load_dwordx2 v[32:33], v[86:87], off
	global_load_dwordx2 v[36:37], v[86:87], off offset:1536
	global_load_dword v34, v[90:91], off
	global_load_dwordx2 v[42:43], v[82:83], off offset:768
	global_load_dwordx2 v[44:45], v[82:83], off
	global_load_dwordx2 v[46:47], v[88:89], off
	global_load_dwordx2 v[48:49], v[88:89], off offset:1536
	global_load_dword v35, v[92:93], off
	global_load_dword v65, v[84:85], off offset:1536
	v_mov_b32_e32 v50, v12
